# EpiG1: hoist the 8 per-row rss loads to epilogue top, drop per-iteration vmcnt(0)
# speedup vs baseline: 1.0130x; 1.0130x over previous
.LBB0_432:
	v_lshl_add_u32 v158, s34, 8, v166
	v_ashrrev_i32_e32 v159, 31, v158
	v_lshlrev_b64 v[160:161], 6, v[158:159]
	v_lshl_add_u64 v[160:161], v[150:151], 0, v[160:161]
	global_load_dwordx4 v[176:179], v[160:161], off offset:1024
	global_load_dwordx4 v[180:183], v[160:161], off offset:2048
	global_load_dwordx4 v[186:189], v[160:161], off offset:3072
	s_mov_b32 s98, 0x2000
	s_mov_b32 s99, 0
	v_lshl_add_u64 v[190:191], v[160:161], 0, s[98:99]
	global_load_dwordx4 v[198:201], v[190:191], off
	global_load_dwordx4 v[202:205], v[190:191], off offset:1024
	global_load_dwordx4 v[206:209], v[190:191], off offset:2048
	global_load_dwordx4 v[210:213], v[190:191], off offset:3072
	global_load_dwordx4 v[160:163], v[160:161], off
	v_and_b32_e32 v165, 64, v221
	v_xor_b32_e32 v164, 16, v221
	v_add_u32_e32 v165, 64, v165
	v_cmp_lt_i32_e32 vcc, v164, v165
	s_waitcnt vmcnt(0)
	v_add_f32_e32 v160, v160, v161
	v_cndmask_b32_e32 v164, v221, v164, vcc
	v_add_f32_e32 v161, v162, v163
	v_lshlrev_b32_e32 v170, 2, v164
	v_add_f32_e32 v160, v160, v161
	ds_bpermute_b32 v161, v170, v160
	v_xor_b32_e32 v162, 32, v221
	v_cmp_lt_i32_e32 vcc, v162, v165
	s_waitcnt lgkmcnt(0)
	v_add_f32_e32 v160, v160, v161
	v_cndmask_b32_e32 v162, v221, v162, vcc
	v_lshlrev_b32_e32 v171, 2, v162
	ds_bpermute_b32 v161, v171, v160
	v_cndmask_b32_e64 v162, 0, 1, s[36:37]
	v_cmp_ne_u32_e64 s[74:75], 1, v162
	s_andn2_b64 vcc, exec, s[36:37]
	s_cbranch_vccnz .LBB0_434
	v_mov_b32_e32 v44, s53
	v_mov_b32_e32 v45, s54
	v_cmp_gt_i32_e32 vcc, s33, v158
	s_mov_b32 s25, 0x9000
	s_nop 0
	v_cndmask_b32_e32 v44, v44, v45, vcc
	v_add_u32_e32 v44, v158, v44
	v_add_u32_e32 v46, 0xffffc000, v44
	v_lshrrev_b32_e32 v46, 3, v46
	v_ashrrev_i32_e32 v45, 11, v44
	v_add_u32_e32 v46, 8, v46
	v_cmp_gt_i32_e32 vcc, s90, v44
	s_nop 1
	v_cndmask_b32_e32 v46, v46, v45, vcc
	v_mov_b64_e32 v[44:45], s[8:9]
	v_mad_i64_i32 v[44:45], s[34:35], v46, s25, v[44:45]
	v_lshl_add_u64 v[52:53], v[156:157], 2, v[44:45]
	global_load_dwordx4 v[60:63], v[52:53], off offset:16
	global_load_dwordx4 v[56:59], v[52:53], off
	global_load_dwordx4 v[44:47], v[52:53], off offset:528
	s_nop 0
	global_load_dwordx4 v[52:55], v[52:53], off offset:512
	s_branch .LBB0_435

.LBB0_449:
	v_or_b32_e32 v128, 16, v158
	v_ashrrev_i32_e32 v129, 31, v128
	s_waitcnt lgkmcnt(0)
	s_and_b64 vcc, exec, s[74:75]
	v_add_f32_e32 v130, v176, v177
	v_add_f32_e32 v131, v178, v179
	v_add_f32_e32 v130, v130, v131
	ds_bpermute_b32 v131, v170, v130
	s_waitcnt lgkmcnt(0)
	v_add_f32_e32 v130, v130, v131
	ds_bpermute_b32 v131, v171, v130
	s_cbranch_vccnz .LBB0_451
	v_add_u32_e32 v44, s54, v128
	v_add_u32_e32 v45, s55, v158
	v_cmp_gt_i32_e32 vcc, s33, v128
	s_nop 1
	v_cndmask_b32_e32 v44, v45, v44, vcc
	v_add_u32_e32 v46, 0xffffc000, v44
	v_lshrrev_b32_e32 v46, 3, v46
	v_ashrrev_i32_e32 v45, 11, v44
	v_add_u32_e32 v46, 8, v46
	v_cmp_gt_i32_e32 vcc, s90, v44
	s_nop 1
	v_cndmask_b32_e32 v46, v46, v45, vcc
	v_mov_b64_e32 v[44:45], s[8:9]
	v_mad_i64_i32 v[44:45], s[30:31], v46, s25, v[44:45]
	v_lshl_add_u64 v[52:53], v[156:157], 2, v[44:45]
	global_load_dwordx4 v[60:63], v[52:53], off offset:16
	global_load_dwordx4 v[56:59], v[52:53], off
	global_load_dwordx4 v[44:47], v[52:53], off offset:528
	s_nop 0
	global_load_dwordx4 v[52:55], v[52:53], off offset:512

.LBB0_465:
	v_or_b32_e32 v112, 32, v158
	v_ashrrev_i32_e32 v113, 31, v112
	s_waitcnt lgkmcnt(0)
	s_and_b64 vcc, exec, s[74:75]
	v_add_f32_e32 v114, v180, v181
	v_add_f32_e32 v115, v182, v183
	v_add_f32_e32 v114, v114, v115
	ds_bpermute_b32 v115, v170, v114
	s_waitcnt lgkmcnt(0)
	v_add_f32_e32 v114, v114, v115
	ds_bpermute_b32 v115, v171, v114
	s_cbranch_vccnz .LBB0_467
	v_add_u32_e32 v44, s54, v112
	v_add_u32_e32 v45, s56, v158
	v_cmp_gt_i32_e32 vcc, s33, v112
	s_nop 1
	v_cndmask_b32_e32 v44, v45, v44, vcc
	v_add_u32_e32 v46, 0xffffc000, v44
	v_lshrrev_b32_e32 v46, 3, v46
	v_ashrrev_i32_e32 v45, 11, v44
	v_add_u32_e32 v46, 8, v46
	v_cmp_gt_i32_e32 vcc, s90, v44
	s_nop 1
	v_cndmask_b32_e32 v46, v46, v45, vcc
	v_mov_b64_e32 v[44:45], s[8:9]
	v_mad_i64_i32 v[44:45], s[30:31], v46, s25, v[44:45]
	v_lshl_add_u64 v[52:53], v[156:157], 2, v[44:45]
	global_load_dwordx4 v[60:63], v[52:53], off offset:16
	global_load_dwordx4 v[56:59], v[52:53], off
	global_load_dwordx4 v[44:47], v[52:53], off offset:528
	s_nop 0
	global_load_dwordx4 v[52:55], v[52:53], off offset:512

.LBB0_481:
	v_or_b32_e32 v96, 48, v158
	v_ashrrev_i32_e32 v97, 31, v96
	s_waitcnt lgkmcnt(0)
	s_and_b64 vcc, exec, s[74:75]
	v_add_f32_e32 v98, v186, v187
	v_add_f32_e32 v99, v188, v189
	v_add_f32_e32 v98, v98, v99
	ds_bpermute_b32 v99, v170, v98
	s_waitcnt lgkmcnt(0)
	v_add_f32_e32 v98, v98, v99
	ds_bpermute_b32 v99, v171, v98
	s_cbranch_vccnz .LBB0_483
	v_add_u32_e32 v44, s54, v96
	v_add_u32_e32 v45, s57, v158
	v_cmp_gt_i32_e32 vcc, s33, v96
	s_nop 1
	v_cndmask_b32_e32 v44, v45, v44, vcc
	v_add_u32_e32 v46, 0xffffc000, v44
	v_lshrrev_b32_e32 v46, 3, v46
	v_ashrrev_i32_e32 v45, 11, v44
	v_add_u32_e32 v46, 8, v46
	v_cmp_gt_i32_e32 vcc, s90, v44
	s_nop 1
	v_cndmask_b32_e32 v46, v46, v45, vcc
	v_mov_b64_e32 v[44:45], s[8:9]
	v_mad_i64_i32 v[44:45], s[30:31], v46, s25, v[44:45]
	v_lshl_add_u64 v[52:53], v[156:157], 2, v[44:45]
	global_load_dwordx4 v[60:63], v[52:53], off offset:16
	global_load_dwordx4 v[56:59], v[52:53], off
	global_load_dwordx4 v[44:47], v[52:53], off offset:528
	s_nop 0
	global_load_dwordx4 v[52:55], v[52:53], off offset:512

.LBB0_497:
	v_add_u32_e32 v80, 0x80, v158
	v_ashrrev_i32_e32 v81, 31, v80
	s_waitcnt lgkmcnt(0)
	s_and_b64 vcc, exec, s[74:75]
	v_add_f32_e32 v82, v198, v199
	v_add_f32_e32 v83, v200, v201
	v_add_f32_e32 v82, v82, v83
	ds_bpermute_b32 v83, v170, v82
	s_waitcnt lgkmcnt(0)
	v_add_f32_e32 v82, v82, v83
	ds_bpermute_b32 v83, v171, v82
	s_cbranch_vccnz .LBB0_499
	v_add_u32_e32 v44, s54, v80
	v_add_u32_e32 v45, s58, v158
	v_cmp_gt_i32_e32 vcc, s33, v80
	s_nop 1
	v_cndmask_b32_e32 v44, v45, v44, vcc
	v_add_u32_e32 v46, 0xffffc000, v44
	v_lshrrev_b32_e32 v46, 3, v46
	v_ashrrev_i32_e32 v45, 11, v44
	v_add_u32_e32 v46, 8, v46
	v_cmp_gt_i32_e32 vcc, s90, v44
	s_nop 1
	v_cndmask_b32_e32 v46, v46, v45, vcc
	v_mov_b64_e32 v[44:45], s[8:9]
	v_mad_i64_i32 v[44:45], s[30:31], v46, s25, v[44:45]
	v_lshl_add_u64 v[52:53], v[156:157], 2, v[44:45]
	global_load_dwordx4 v[60:63], v[52:53], off offset:16
	global_load_dwordx4 v[56:59], v[52:53], off
	global_load_dwordx4 v[44:47], v[52:53], off offset:528
	s_nop 0
	global_load_dwordx4 v[52:55], v[52:53], off offset:512

.LBB0_513:
	v_add_u32_e32 v64, 0x90, v158
	v_ashrrev_i32_e32 v65, 31, v64
	s_waitcnt lgkmcnt(0)
	s_and_b64 vcc, exec, s[74:75]
	v_add_f32_e32 v66, v202, v203
	v_add_f32_e32 v67, v204, v205
	v_add_f32_e32 v66, v66, v67
	ds_bpermute_b32 v67, v170, v66
	s_waitcnt lgkmcnt(0)
	v_add_f32_e32 v66, v66, v67
	ds_bpermute_b32 v67, v171, v66
	s_cbranch_vccnz .LBB0_515
	v_add_u32_e32 v44, s54, v64
	v_add_u32_e32 v45, s59, v158
	v_cmp_gt_i32_e32 vcc, s33, v64
	s_nop 1
	v_cndmask_b32_e32 v44, v45, v44, vcc
	v_add_u32_e32 v46, 0xffffc000, v44
	v_lshrrev_b32_e32 v46, 3, v46
	v_ashrrev_i32_e32 v45, 11, v44
	v_add_u32_e32 v46, 8, v46
	v_cmp_gt_i32_e32 vcc, s90, v44
	s_nop 1
	v_cndmask_b32_e32 v46, v46, v45, vcc
	v_mov_b64_e32 v[44:45], s[8:9]
	v_mad_i64_i32 v[44:45], s[30:31], v46, s25, v[44:45]
	v_lshl_add_u64 v[52:53], v[156:157], 2, v[44:45]
	global_load_dwordx4 v[60:63], v[52:53], off offset:16
	global_load_dwordx4 v[56:59], v[52:53], off
	global_load_dwordx4 v[44:47], v[52:53], off offset:528
	s_nop 0
	global_load_dwordx4 v[52:55], v[52:53], off offset:512

.LBB0_529:
	v_add_u32_e32 v32, 0xa0, v158
	v_ashrrev_i32_e32 v33, 31, v32
	s_waitcnt lgkmcnt(0)
	s_and_b64 vcc, exec, s[74:75]
	v_add_f32_e32 v34, v206, v207
	v_add_f32_e32 v35, v208, v209
	v_add_f32_e32 v34, v34, v35
	ds_bpermute_b32 v35, v170, v34
	s_waitcnt lgkmcnt(0)
	v_add_f32_e32 v34, v34, v35
	ds_bpermute_b32 v35, v171, v34
	s_cbranch_vccnz .LBB0_531
	v_add_u32_e32 v36, s54, v32
	v_add_u32_e32 v37, s60, v158
	v_cmp_gt_i32_e32 vcc, s33, v32
	s_nop 1
	v_cndmask_b32_e32 v36, v37, v36, vcc
	v_add_u32_e32 v38, 0xffffc000, v36
	v_lshrrev_b32_e32 v38, 3, v38
	v_ashrrev_i32_e32 v37, 11, v36
	v_add_u32_e32 v38, 8, v38
	v_cmp_gt_i32_e32 vcc, s90, v36
	s_nop 1
	v_cndmask_b32_e32 v38, v38, v37, vcc
	v_mov_b64_e32 v[36:37], s[8:9]
	v_mad_i64_i32 v[36:37], s[30:31], v38, s25, v[36:37]
	v_lshl_add_u64 v[36:37], v[156:157], 2, v[36:37]
	global_load_dwordx4 v[60:63], v[36:37], off offset:16
	global_load_dwordx4 v[56:59], v[36:37], off
	global_load_dwordx4 v[44:47], v[36:37], off offset:528
	global_load_dwordx4 v[52:55], v[36:37], off offset:512

.LBB0_545:
	v_add_u32_e32 v16, 0xb0, v158
	v_ashrrev_i32_e32 v17, 31, v16
	s_waitcnt lgkmcnt(0)
	s_and_b64 vcc, exec, s[74:75]
	v_add_f32_e32 v18, v210, v211
	v_add_f32_e32 v19, v212, v213
	v_add_f32_e32 v18, v18, v19
	ds_bpermute_b32 v19, v170, v18
	s_waitcnt lgkmcnt(0)
	v_add_f32_e32 v18, v18, v19
	ds_bpermute_b32 v19, v171, v18
	s_cbranch_vccnz .LBB0_547
	v_add_u32_e32 v20, s54, v16
	v_add_u32_e32 v21, s61, v158
	v_cmp_gt_i32_e32 vcc, s33, v16
	s_nop 1
	v_cndmask_b32_e32 v20, v21, v20, vcc
	v_add_u32_e32 v22, 0xffffc000, v20
	v_lshrrev_b32_e32 v22, 3, v22
	v_ashrrev_i32_e32 v21, 11, v20
	v_add_u32_e32 v22, 8, v22
	v_cmp_gt_i32_e32 vcc, s90, v20
	s_nop 1
	v_cndmask_b32_e32 v22, v22, v21, vcc
	v_mov_b64_e32 v[20:21], s[8:9]
	v_mad_i64_i32 v[20:21], s[30:31], v22, s25, v[20:21]
	v_lshl_add_u64 v[20:21], v[156:157], 2, v[20:21]
	global_load_dwordx4 v[60:63], v[20:21], off offset:16
	global_load_dwordx4 v[56:59], v[20:21], off
	global_load_dwordx4 v[44:47], v[20:21], off offset:528
	global_load_dwordx4 v[52:55], v[20:21], off offset:512
